# GEMM K-loop duplicated: waves 4-7 run it with every s_setprio level raised by one (static priority raise for the younger half), waves 0-3 unchanged
# baseline (speedup 1.0000x reference)
.LBB0_332:
	s_cmp_lg_u64 s[10:11], 0
	s_cbranch_scc1 .Lgemm_raised
.Lgemm_plain:
	s_add_i32 s69, s64, 2
	s_add_u32 s85, s8, 0x80
	s_addc_u32 s65, s9, 0
	s_add_i32 s80, 0, 0x10000
	s_cmp_eq_u32 s19, s64
	s_cselect_b32 s65, s15, s65
	s_cselect_b32 s64, s14, s85
	s_cselect_b32 vcc_hi, s83, s68
	s_cselect_b32 vcc_lo, s82, s16
	s_add_i32 s81, 0, 0x14000
	v_add_u32_e32 v140, s80, v206
	v_add_u32_e32 v156, s81, v206
	ds_read_b128 v[128:131], v140
	ds_read_b128 v[132:135], v140 offset:1024
	ds_read_b128 v[136:139], v140 offset:2048
	ds_read_b128 v[140:143], v140 offset:3072
	ds_read_b128 v[144:147], v156
	ds_read_b128 v[148:151], v156 offset:1024
	ds_read_b128 v[152:155], v156 offset:2048
	ds_read_b128 v[156:159], v156 offset:3072
	v_lshl_add_u64 v[198:199], s[8:9], 0, v[186:187]
	s_add_i32 m0, s73, 0xc000
	ds_read_b128 v[160:163], v211
	ds_read_b128 v[164:167], v211 offset:1024
	ds_read_b128 v[190:193], v211 offset:2048
	ds_read_b128 v[194:197], v211 offset:3072
	ds_read_b128 v[212:215], v211 offset:4096
	ds_read_b128 v[216:219], v211 offset:5120
	ds_read_b128 v[220:223], v211 offset:6144
	ds_read_b128 v[224:227], v211 offset:7168
	global_load_lds_dwordx4 v[198:199], off
	v_lshl_add_u64 v[198:199], s[8:9], 0, v[188:189]
	s_add_i32 m0, s73, 0xe000
	s_nop 0
	global_load_lds_dwordx4 v[198:199], off
	s_waitcnt vmcnt(8)
	s_waitcnt lgkmcnt(0)
	s_barrier
	s_setprio 1
	s_waitcnt lgkmcnt(0)
	v_mfma_f32_16x16x32_bf16 v[124:127], v[128:131], v[160:163], v[124:127]
	v_mfma_f32_16x16x32_bf16 v[120:123], v[136:139], v[160:163], v[120:123]
	v_mfma_f32_16x16x32_bf16 v[108:111], v[128:131], v[190:193], v[108:111]
	v_mfma_f32_16x16x32_bf16 v[104:107], v[136:139], v[190:193], v[104:107]
	v_mfma_f32_16x16x32_bf16 v[92:95], v[128:131], v[212:215], v[92:95]
	v_mfma_f32_16x16x32_bf16 v[88:91], v[136:139], v[212:215], v[88:91]
	v_mfma_f32_16x16x32_bf16 v[76:79], v[128:131], v[220:223], v[76:79]
	v_mfma_f32_16x16x32_bf16 v[72:75], v[136:139], v[220:223], v[72:75]
	v_mfma_f32_16x16x32_bf16 v[124:127], v[132:135], v[164:167], v[124:127]
	v_mfma_f32_16x16x32_bf16 v[120:123], v[140:143], v[164:167], v[120:123]
	v_mfma_f32_16x16x32_bf16 v[108:111], v[132:135], v[194:197], v[108:111]
	v_mfma_f32_16x16x32_bf16 v[104:107], v[140:143], v[194:197], v[104:107]
	v_mfma_f32_16x16x32_bf16 v[92:95], v[132:135], v[216:219], v[92:95]
	v_mfma_f32_16x16x32_bf16 v[88:91], v[140:143], v[216:219], v[88:91]
	v_mfma_f32_16x16x32_bf16 v[76:79], v[132:135], v[224:227], v[76:79]
	v_mfma_f32_16x16x32_bf16 v[72:75], v[140:143], v[224:227], v[72:75]
	s_setprio 0
	s_setprio 1
	v_mfma_f32_16x16x32_bf16 v[116:119], v[144:147], v[160:163], v[116:119]
	v_mfma_f32_16x16x32_bf16 v[112:115], v[152:155], v[160:163], v[112:115]
	v_mfma_f32_16x16x32_bf16 v[100:103], v[144:147], v[190:193], v[100:103]
	v_mfma_f32_16x16x32_bf16 v[96:99], v[152:155], v[190:193], v[96:99]
	v_mfma_f32_16x16x32_bf16 v[84:87], v[144:147], v[212:215], v[84:87]
	v_mfma_f32_16x16x32_bf16 v[80:83], v[152:155], v[212:215], v[80:83]
	v_mfma_f32_16x16x32_bf16 v[68:71], v[144:147], v[220:223], v[68:71]
	v_mfma_f32_16x16x32_bf16 v[64:67], v[152:155], v[220:223], v[64:67]
	v_mfma_f32_16x16x32_bf16 v[116:119], v[148:151], v[164:167], v[116:119]
	v_mfma_f32_16x16x32_bf16 v[112:115], v[156:159], v[164:167], v[112:115]
	v_mfma_f32_16x16x32_bf16 v[100:103], v[148:151], v[194:197], v[100:103]
	v_mfma_f32_16x16x32_bf16 v[96:99], v[156:159], v[194:197], v[96:99]
	v_mfma_f32_16x16x32_bf16 v[84:87], v[148:151], v[216:219], v[84:87]
	v_mfma_f32_16x16x32_bf16 v[80:83], v[156:159], v[216:219], v[80:83]
	v_mfma_f32_16x16x32_bf16 v[68:71], v[148:151], v[224:227], v[68:71]
	v_mfma_f32_16x16x32_bf16 v[64:67], v[156:159], v[224:227], v[64:67]
	s_setprio 0
	s_barrier
	s_add_i32 s80, s80, s72
	v_lshl_add_u64 v[198:199], vcc, 0, v[176:177]
	s_mov_b32 m0, s80
	ds_read_b128 v[160:163], v211 offset:16384
	ds_read_b128 v[164:167], v211 offset:17408
	ds_read_b128 v[190:193], v211 offset:18432
	ds_read_b128 v[194:197], v211 offset:19456
	ds_read_b128 v[212:215], v211 offset:20480
	ds_read_b128 v[216:219], v211 offset:21504
	ds_read_b128 v[220:223], v211 offset:22528
	ds_read_b128 v[224:227], v211 offset:23552
	global_load_lds_dwordx4 v[198:199], off
	s_add_i32 m0, s80, 0x2000
	v_lshl_add_u64 v[228:229], vcc, 0, v[180:181]
	s_add_u32 vcc_lo, vcc_lo, s74
	s_addc_u32 vcc_hi, vcc_hi, 0
	s_add_i32 s80, s81, s72
	global_load_lds_dwordx4 v[228:229], off
	v_lshl_add_u64 v[230:231], vcc, 0, v[176:177]
	s_mov_b32 m0, s80
	v_lshl_add_u64 v[232:233], vcc, 0, v[180:181]
	global_load_lds_dwordx4 v[230:231], off
	s_add_i32 m0, s80, 0x2000
	v_lshl_add_u64 v[234:235], s[64:65], 0, v[174:175]
	global_load_lds_dwordx4 v[232:233], off
	s_mov_b32 m0, s73
	v_lshl_add_u64 v[236:237], s[64:65], 0, v[178:179]
	global_load_lds_dwordx4 v[234:235], off
	s_mov_b32 m0, s92
	s_nop 0
	global_load_lds_dwordx4 v[236:237], off
	s_waitcnt vmcnt(8)
	s_waitcnt lgkmcnt(0)
	s_barrier
	s_setprio 1
	s_waitcnt lgkmcnt(0)
	v_mfma_f32_16x16x32_bf16 v[60:63], v[128:131], v[160:163], v[60:63]
	v_mfma_f32_16x16x32_bf16 v[56:59], v[136:139], v[160:163], v[56:59]
	v_mfma_f32_16x16x32_bf16 v[44:47], v[128:131], v[190:193], v[44:47]
	v_mfma_f32_16x16x32_bf16 v[40:43], v[136:139], v[190:193], v[40:43]
	v_mfma_f32_16x16x32_bf16 v[28:31], v[128:131], v[212:215], v[28:31]
	v_mfma_f32_16x16x32_bf16 v[24:27], v[136:139], v[212:215], v[24:27]
	v_mfma_f32_16x16x32_bf16 v[12:15], v[128:131], v[220:223], v[12:15]
	v_mfma_f32_16x16x32_bf16 v[8:11], v[136:139], v[220:223], v[8:11]
	v_mfma_f32_16x16x32_bf16 v[60:63], v[132:135], v[164:167], v[60:63]
	v_mfma_f32_16x16x32_bf16 v[56:59], v[140:143], v[164:167], v[56:59]
	v_mfma_f32_16x16x32_bf16 v[44:47], v[132:135], v[194:197], v[44:47]
	v_mfma_f32_16x16x32_bf16 v[40:43], v[140:143], v[194:197], v[40:43]
	v_mfma_f32_16x16x32_bf16 v[28:31], v[132:135], v[216:219], v[28:31]
	v_mfma_f32_16x16x32_bf16 v[24:27], v[140:143], v[216:219], v[24:27]
	v_mfma_f32_16x16x32_bf16 v[12:15], v[132:135], v[224:227], v[12:15]
	v_mfma_f32_16x16x32_bf16 v[8:11], v[140:143], v[224:227], v[8:11]
	s_setprio 0
	s_setprio 1
	v_mfma_f32_16x16x32_bf16 v[52:55], v[144:147], v[160:163], v[52:55]
	v_mfma_f32_16x16x32_bf16 v[48:51], v[152:155], v[160:163], v[48:51]
	v_mfma_f32_16x16x32_bf16 v[36:39], v[144:147], v[190:193], v[36:39]
	v_mfma_f32_16x16x32_bf16 v[32:35], v[152:155], v[190:193], v[32:35]
	v_mfma_f32_16x16x32_bf16 v[20:23], v[144:147], v[212:215], v[20:23]
	v_mfma_f32_16x16x32_bf16 v[16:19], v[152:155], v[212:215], v[16:19]
	v_mfma_f32_16x16x32_bf16 v[4:7], v[144:147], v[220:223], v[4:7]
	v_mfma_f32_16x16x32_bf16 v[0:3], v[152:155], v[220:223], v[0:3]
	v_mfma_f32_16x16x32_bf16 v[52:55], v[148:151], v[164:167], v[52:55]
	v_mfma_f32_16x16x32_bf16 v[48:51], v[156:159], v[164:167], v[48:51]
	v_mfma_f32_16x16x32_bf16 v[36:39], v[148:151], v[194:197], v[36:39]
	v_mfma_f32_16x16x32_bf16 v[32:35], v[156:159], v[194:197], v[32:35]
	v_mfma_f32_16x16x32_bf16 v[20:23], v[148:151], v[216:219], v[20:23]
	v_mfma_f32_16x16x32_bf16 v[16:19], v[156:159], v[216:219], v[16:19]
	v_mfma_f32_16x16x32_bf16 v[4:7], v[148:151], v[224:227], v[4:7]
	v_mfma_f32_16x16x32_bf16 v[0:3], v[156:159], v[224:227], v[0:3]
	s_setprio 0
	s_barrier
	s_add_i32 s80, 0, 0x18000
	s_add_i32 s81, 0, 0x1c000
	v_add_u32_e32 v140, s80, v206
	v_add_u32_e32 v156, s81, v206
	ds_read_b128 v[128:131], v140
	ds_read_b128 v[132:135], v140 offset:1024
	ds_read_b128 v[136:139], v140 offset:2048
	ds_read_b128 v[140:143], v140 offset:3072
	ds_read_b128 v[144:147], v156
	ds_read_b128 v[148:151], v156 offset:1024
	ds_read_b128 v[152:155], v156 offset:2048
	ds_read_b128 v[156:159], v156 offset:3072
	s_add_u32 s64, s64, s74
	s_addc_u32 s65, s65, 0
	s_mov_b32 m0, s93
	v_lshl_add_u64 v[238:239], s[64:65], 0, v[174:175]
	ds_read_b128 v[160:163], v211 offset:32768
	ds_read_b128 v[164:167], v211 offset:33792
	ds_read_b128 v[190:193], v211 offset:34816
	ds_read_b128 v[194:197], v211 offset:35840
	ds_read_b128 v[212:215], v211 offset:36864
	ds_read_b128 v[216:219], v211 offset:37888
	ds_read_b128 v[220:223], v211 offset:38912
	ds_read_b128 v[224:227], v211 offset:39936
	global_load_lds_dwordx4 v[238:239], off
	v_lshl_add_u64 v[238:239], s[64:65], 0, v[178:179]
	s_mov_b32 m0, s94
	s_nop 0
	global_load_lds_dwordx4 v[238:239], off
	s_waitcnt vmcnt(8)
	s_waitcnt lgkmcnt(0)
	s_barrier
	s_setprio 1
	s_waitcnt lgkmcnt(0)
	v_mfma_f32_16x16x32_bf16 v[124:127], v[128:131], v[160:163], v[124:127]
	v_mfma_f32_16x16x32_bf16 v[120:123], v[136:139], v[160:163], v[120:123]
	v_mfma_f32_16x16x32_bf16 v[108:111], v[128:131], v[190:193], v[108:111]
	v_mfma_f32_16x16x32_bf16 v[104:107], v[136:139], v[190:193], v[104:107]
	v_mfma_f32_16x16x32_bf16 v[92:95], v[128:131], v[212:215], v[92:95]
	v_mfma_f32_16x16x32_bf16 v[88:91], v[136:139], v[212:215], v[88:91]
	v_mfma_f32_16x16x32_bf16 v[76:79], v[128:131], v[220:223], v[76:79]
	v_mfma_f32_16x16x32_bf16 v[72:75], v[136:139], v[220:223], v[72:75]
	v_mfma_f32_16x16x32_bf16 v[124:127], v[132:135], v[164:167], v[124:127]
	v_mfma_f32_16x16x32_bf16 v[120:123], v[140:143], v[164:167], v[120:123]
	v_mfma_f32_16x16x32_bf16 v[108:111], v[132:135], v[194:197], v[108:111]
	v_mfma_f32_16x16x32_bf16 v[104:107], v[140:143], v[194:197], v[104:107]
	v_mfma_f32_16x16x32_bf16 v[92:95], v[132:135], v[216:219], v[92:95]
	v_mfma_f32_16x16x32_bf16 v[88:91], v[140:143], v[216:219], v[88:91]
	v_mfma_f32_16x16x32_bf16 v[76:79], v[132:135], v[224:227], v[76:79]
	v_mfma_f32_16x16x32_bf16 v[72:75], v[140:143], v[224:227], v[72:75]
	s_setprio 0
	s_setprio 1
	v_mfma_f32_16x16x32_bf16 v[116:119], v[144:147], v[160:163], v[116:119]
	v_mfma_f32_16x16x32_bf16 v[112:115], v[152:155], v[160:163], v[112:115]
	v_mfma_f32_16x16x32_bf16 v[100:103], v[144:147], v[190:193], v[100:103]
	v_mfma_f32_16x16x32_bf16 v[96:99], v[152:155], v[190:193], v[96:99]
	v_mfma_f32_16x16x32_bf16 v[84:87], v[144:147], v[212:215], v[84:87]
	v_mfma_f32_16x16x32_bf16 v[80:83], v[152:155], v[212:215], v[80:83]
	v_mfma_f32_16x16x32_bf16 v[68:71], v[144:147], v[220:223], v[68:71]
	v_mfma_f32_16x16x32_bf16 v[64:67], v[152:155], v[220:223], v[64:67]
	v_mfma_f32_16x16x32_bf16 v[116:119], v[148:151], v[164:167], v[116:119]
	v_mfma_f32_16x16x32_bf16 v[112:115], v[156:159], v[164:167], v[112:115]
	v_mfma_f32_16x16x32_bf16 v[100:103], v[148:151], v[194:197], v[100:103]
	v_mfma_f32_16x16x32_bf16 v[96:99], v[156:159], v[194:197], v[96:99]
	v_mfma_f32_16x16x32_bf16 v[84:87], v[148:151], v[216:219], v[84:87]
	v_mfma_f32_16x16x32_bf16 v[80:83], v[156:159], v[216:219], v[80:83]
	v_mfma_f32_16x16x32_bf16 v[68:71], v[148:151], v[224:227], v[68:71]
	v_mfma_f32_16x16x32_bf16 v[64:67], v[156:159], v[224:227], v[64:67]
	s_setprio 0
	s_barrier
	s_add_i32 s64, s80, s72
	v_lshl_add_u64 v[198:199], v[198:199], 0, s[88:89]
	s_mov_b32 m0, s64
	ds_read_b128 v[160:163], v211 offset:49152
	ds_read_b128 v[164:167], v211 offset:50176
	ds_read_b128 v[190:193], v211 offset:51200
	ds_read_b128 v[194:197], v211 offset:52224
	ds_read_b128 v[212:215], v211 offset:53248
	ds_read_b128 v[216:219], v211 offset:54272
	ds_read_b128 v[220:223], v211 offset:55296
	ds_read_b128 v[224:227], v211 offset:56320
	global_load_lds_dwordx4 v[198:199], off
	v_lshl_add_u64 v[198:199], v[228:229], 0, s[88:89]
	s_add_i32 m0, s64, 0x2000
	s_add_i32 s64, s81, s72
	global_load_lds_dwordx4 v[198:199], off
	v_lshl_add_u64 v[198:199], v[230:231], 0, s[88:89]
	s_mov_b32 m0, s64
	s_nop 0
	global_load_lds_dwordx4 v[198:199], off
	v_lshl_add_u64 v[198:199], v[232:233], 0, s[88:89]
	s_add_i32 m0, s64, 0x2000
	s_nop 0
	global_load_lds_dwordx4 v[198:199], off
	v_lshl_add_u64 v[198:199], v[234:235], 0, s[88:89]
	s_mov_b32 m0, s95
	s_nop 0
	global_load_lds_dwordx4 v[198:199], off
	v_lshl_add_u64 v[198:199], v[236:237], 0, s[88:89]
	s_mov_b32 m0, s98
	s_nop 0
	global_load_lds_dwordx4 v[198:199], off
	s_waitcnt vmcnt(8)
	s_waitcnt lgkmcnt(0)
	s_barrier
	s_setprio 1
	s_waitcnt lgkmcnt(0)
	v_mfma_f32_16x16x32_bf16 v[60:63], v[128:131], v[160:163], v[60:63]
	v_mfma_f32_16x16x32_bf16 v[56:59], v[136:139], v[160:163], v[56:59]
	v_mfma_f32_16x16x32_bf16 v[44:47], v[128:131], v[190:193], v[44:47]
	v_mfma_f32_16x16x32_bf16 v[40:43], v[136:139], v[190:193], v[40:43]
	v_mfma_f32_16x16x32_bf16 v[28:31], v[128:131], v[212:215], v[28:31]
	v_mfma_f32_16x16x32_bf16 v[24:27], v[136:139], v[212:215], v[24:27]
	v_mfma_f32_16x16x32_bf16 v[12:15], v[128:131], v[220:223], v[12:15]
	v_mfma_f32_16x16x32_bf16 v[8:11], v[136:139], v[220:223], v[8:11]
	v_mfma_f32_16x16x32_bf16 v[60:63], v[132:135], v[164:167], v[60:63]
	v_mfma_f32_16x16x32_bf16 v[56:59], v[140:143], v[164:167], v[56:59]
	v_mfma_f32_16x16x32_bf16 v[44:47], v[132:135], v[194:197], v[44:47]
	v_mfma_f32_16x16x32_bf16 v[40:43], v[140:143], v[194:197], v[40:43]
	v_mfma_f32_16x16x32_bf16 v[28:31], v[132:135], v[216:219], v[28:31]
	v_mfma_f32_16x16x32_bf16 v[24:27], v[140:143], v[216:219], v[24:27]
	v_mfma_f32_16x16x32_bf16 v[12:15], v[132:135], v[224:227], v[12:15]
	v_mfma_f32_16x16x32_bf16 v[8:11], v[140:143], v[224:227], v[8:11]
	s_setprio 0
	s_setprio 1
	v_mfma_f32_16x16x32_bf16 v[52:55], v[144:147], v[160:163], v[52:55]
	v_mfma_f32_16x16x32_bf16 v[48:51], v[152:155], v[160:163], v[48:51]
	v_mfma_f32_16x16x32_bf16 v[36:39], v[144:147], v[190:193], v[36:39]
	v_mfma_f32_16x16x32_bf16 v[32:35], v[152:155], v[190:193], v[32:35]
	v_mfma_f32_16x16x32_bf16 v[20:23], v[144:147], v[212:215], v[20:23]
	v_mfma_f32_16x16x32_bf16 v[16:19], v[152:155], v[212:215], v[16:19]
	v_mfma_f32_16x16x32_bf16 v[4:7], v[144:147], v[220:223], v[4:7]
	v_mfma_f32_16x16x32_bf16 v[0:3], v[152:155], v[220:223], v[0:3]
	v_mfma_f32_16x16x32_bf16 v[52:55], v[148:151], v[164:167], v[52:55]
	v_mfma_f32_16x16x32_bf16 v[48:51], v[156:159], v[164:167], v[48:51]
	v_mfma_f32_16x16x32_bf16 v[36:39], v[148:151], v[194:197], v[36:39]
	v_mfma_f32_16x16x32_bf16 v[32:35], v[156:159], v[194:197], v[32:35]
	v_mfma_f32_16x16x32_bf16 v[20:23], v[148:151], v[216:219], v[20:23]
	v_mfma_f32_16x16x32_bf16 v[16:19], v[156:159], v[216:219], v[16:19]
	v_mfma_f32_16x16x32_bf16 v[4:7], v[148:151], v[224:227], v[4:7]
	v_mfma_f32_16x16x32_bf16 v[0:3], v[156:159], v[224:227], v[0:3]
	s_setprio 0
	s_barrier
	s_add_u32 s8, s8, 0x100
	s_addc_u32 s9, s9, 0
	s_add_u32 s16, s16, 0x100
	s_addc_u32 s68, s68, 0
	s_cmp_ge_u32 s69, s96
	s_mov_b32 s64, s69
	s_cbranch_scc0 .Lgemm_plain
	s_branch .Lgemm_done
.Lgemm_raised:
	s_add_i32 s69, s64, 2
	s_add_u32 s85, s8, 0x80
	s_addc_u32 s65, s9, 0
	s_add_i32 s80, 0, 0x10000
	s_cmp_eq_u32 s19, s64
	s_cselect_b32 s65, s15, s65
	s_cselect_b32 s64, s14, s85
	s_cselect_b32 vcc_hi, s83, s68
	s_cselect_b32 vcc_lo, s82, s16
	s_add_i32 s81, 0, 0x14000
	v_add_u32_e32 v140, s80, v206
	v_add_u32_e32 v156, s81, v206
	ds_read_b128 v[128:131], v140
	ds_read_b128 v[132:135], v140 offset:1024
	ds_read_b128 v[136:139], v140 offset:2048
	ds_read_b128 v[140:143], v140 offset:3072
	ds_read_b128 v[144:147], v156
	ds_read_b128 v[148:151], v156 offset:1024
	ds_read_b128 v[152:155], v156 offset:2048
	ds_read_b128 v[156:159], v156 offset:3072
	v_lshl_add_u64 v[198:199], s[8:9], 0, v[186:187]
	s_add_i32 m0, s73, 0xc000
	ds_read_b128 v[160:163], v211
	ds_read_b128 v[164:167], v211 offset:1024
	ds_read_b128 v[190:193], v211 offset:2048
	ds_read_b128 v[194:197], v211 offset:3072
	ds_read_b128 v[212:215], v211 offset:4096
	ds_read_b128 v[216:219], v211 offset:5120
	ds_read_b128 v[220:223], v211 offset:6144
	ds_read_b128 v[224:227], v211 offset:7168
	global_load_lds_dwordx4 v[198:199], off
	v_lshl_add_u64 v[198:199], s[8:9], 0, v[188:189]
	s_add_i32 m0, s73, 0xe000
	s_nop 0
	global_load_lds_dwordx4 v[198:199], off
	s_waitcnt vmcnt(8)
	s_waitcnt lgkmcnt(0)
	s_barrier
	s_setprio 2
	s_waitcnt lgkmcnt(0)
	v_mfma_f32_16x16x32_bf16 v[124:127], v[128:131], v[160:163], v[124:127]
	v_mfma_f32_16x16x32_bf16 v[120:123], v[136:139], v[160:163], v[120:123]
	v_mfma_f32_16x16x32_bf16 v[108:111], v[128:131], v[190:193], v[108:111]
	v_mfma_f32_16x16x32_bf16 v[104:107], v[136:139], v[190:193], v[104:107]
	v_mfma_f32_16x16x32_bf16 v[92:95], v[128:131], v[212:215], v[92:95]
	v_mfma_f32_16x16x32_bf16 v[88:91], v[136:139], v[212:215], v[88:91]
	v_mfma_f32_16x16x32_bf16 v[76:79], v[128:131], v[220:223], v[76:79]
	v_mfma_f32_16x16x32_bf16 v[72:75], v[136:139], v[220:223], v[72:75]
	v_mfma_f32_16x16x32_bf16 v[124:127], v[132:135], v[164:167], v[124:127]
	v_mfma_f32_16x16x32_bf16 v[120:123], v[140:143], v[164:167], v[120:123]
	v_mfma_f32_16x16x32_bf16 v[108:111], v[132:135], v[194:197], v[108:111]
	v_mfma_f32_16x16x32_bf16 v[104:107], v[140:143], v[194:197], v[104:107]
	v_mfma_f32_16x16x32_bf16 v[92:95], v[132:135], v[216:219], v[92:95]
	v_mfma_f32_16x16x32_bf16 v[88:91], v[140:143], v[216:219], v[88:91]
	v_mfma_f32_16x16x32_bf16 v[76:79], v[132:135], v[224:227], v[76:79]
	v_mfma_f32_16x16x32_bf16 v[72:75], v[140:143], v[224:227], v[72:75]
	s_setprio 1
	s_setprio 2
	v_mfma_f32_16x16x32_bf16 v[116:119], v[144:147], v[160:163], v[116:119]
	v_mfma_f32_16x16x32_bf16 v[112:115], v[152:155], v[160:163], v[112:115]
	v_mfma_f32_16x16x32_bf16 v[100:103], v[144:147], v[190:193], v[100:103]
	v_mfma_f32_16x16x32_bf16 v[96:99], v[152:155], v[190:193], v[96:99]
	v_mfma_f32_16x16x32_bf16 v[84:87], v[144:147], v[212:215], v[84:87]
	v_mfma_f32_16x16x32_bf16 v[80:83], v[152:155], v[212:215], v[80:83]
	v_mfma_f32_16x16x32_bf16 v[68:71], v[144:147], v[220:223], v[68:71]
	v_mfma_f32_16x16x32_bf16 v[64:67], v[152:155], v[220:223], v[64:67]
	v_mfma_f32_16x16x32_bf16 v[116:119], v[148:151], v[164:167], v[116:119]
	v_mfma_f32_16x16x32_bf16 v[112:115], v[156:159], v[164:167], v[112:115]
	v_mfma_f32_16x16x32_bf16 v[100:103], v[148:151], v[194:197], v[100:103]
	v_mfma_f32_16x16x32_bf16 v[96:99], v[156:159], v[194:197], v[96:99]
	v_mfma_f32_16x16x32_bf16 v[84:87], v[148:151], v[216:219], v[84:87]
	v_mfma_f32_16x16x32_bf16 v[80:83], v[156:159], v[216:219], v[80:83]
	v_mfma_f32_16x16x32_bf16 v[68:71], v[148:151], v[224:227], v[68:71]
	v_mfma_f32_16x16x32_bf16 v[64:67], v[156:159], v[224:227], v[64:67]
	s_setprio 1
	s_barrier
	s_add_i32 s80, s80, s72
	v_lshl_add_u64 v[198:199], vcc, 0, v[176:177]
	s_mov_b32 m0, s80
	ds_read_b128 v[160:163], v211 offset:16384
	ds_read_b128 v[164:167], v211 offset:17408
	ds_read_b128 v[190:193], v211 offset:18432
	ds_read_b128 v[194:197], v211 offset:19456
	ds_read_b128 v[212:215], v211 offset:20480
	ds_read_b128 v[216:219], v211 offset:21504
	ds_read_b128 v[220:223], v211 offset:22528
	ds_read_b128 v[224:227], v211 offset:23552
	global_load_lds_dwordx4 v[198:199], off
	s_add_i32 m0, s80, 0x2000
	v_lshl_add_u64 v[228:229], vcc, 0, v[180:181]
	s_add_u32 vcc_lo, vcc_lo, s74
	s_addc_u32 vcc_hi, vcc_hi, 0
	s_add_i32 s80, s81, s72
	global_load_lds_dwordx4 v[228:229], off
	v_lshl_add_u64 v[230:231], vcc, 0, v[176:177]
	s_mov_b32 m0, s80
	v_lshl_add_u64 v[232:233], vcc, 0, v[180:181]
	global_load_lds_dwordx4 v[230:231], off
	s_add_i32 m0, s80, 0x2000
	v_lshl_add_u64 v[234:235], s[64:65], 0, v[174:175]
	global_load_lds_dwordx4 v[232:233], off
	s_mov_b32 m0, s73
	v_lshl_add_u64 v[236:237], s[64:65], 0, v[178:179]
	global_load_lds_dwordx4 v[234:235], off
	s_mov_b32 m0, s92
	s_nop 0
	global_load_lds_dwordx4 v[236:237], off
	s_waitcnt vmcnt(8)
	s_waitcnt lgkmcnt(0)
	s_barrier
	s_setprio 2
	s_waitcnt lgkmcnt(0)
	v_mfma_f32_16x16x32_bf16 v[60:63], v[128:131], v[160:163], v[60:63]
	v_mfma_f32_16x16x32_bf16 v[56:59], v[136:139], v[160:163], v[56:59]
	v_mfma_f32_16x16x32_bf16 v[44:47], v[128:131], v[190:193], v[44:47]
	v_mfma_f32_16x16x32_bf16 v[40:43], v[136:139], v[190:193], v[40:43]
	v_mfma_f32_16x16x32_bf16 v[28:31], v[128:131], v[212:215], v[28:31]
	v_mfma_f32_16x16x32_bf16 v[24:27], v[136:139], v[212:215], v[24:27]
	v_mfma_f32_16x16x32_bf16 v[12:15], v[128:131], v[220:223], v[12:15]
	v_mfma_f32_16x16x32_bf16 v[8:11], v[136:139], v[220:223], v[8:11]
	v_mfma_f32_16x16x32_bf16 v[60:63], v[132:135], v[164:167], v[60:63]
	v_mfma_f32_16x16x32_bf16 v[56:59], v[140:143], v[164:167], v[56:59]
	v_mfma_f32_16x16x32_bf16 v[44:47], v[132:135], v[194:197], v[44:47]
	v_mfma_f32_16x16x32_bf16 v[40:43], v[140:143], v[194:197], v[40:43]
	v_mfma_f32_16x16x32_bf16 v[28:31], v[132:135], v[216:219], v[28:31]
	v_mfma_f32_16x16x32_bf16 v[24:27], v[140:143], v[216:219], v[24:27]
	v_mfma_f32_16x16x32_bf16 v[12:15], v[132:135], v[224:227], v[12:15]
	v_mfma_f32_16x16x32_bf16 v[8:11], v[140:143], v[224:227], v[8:11]
	s_setprio 1
	s_setprio 2
	v_mfma_f32_16x16x32_bf16 v[52:55], v[144:147], v[160:163], v[52:55]
	v_mfma_f32_16x16x32_bf16 v[48:51], v[152:155], v[160:163], v[48:51]
	v_mfma_f32_16x16x32_bf16 v[36:39], v[144:147], v[190:193], v[36:39]
	v_mfma_f32_16x16x32_bf16 v[32:35], v[152:155], v[190:193], v[32:35]
	v_mfma_f32_16x16x32_bf16 v[20:23], v[144:147], v[212:215], v[20:23]
	v_mfma_f32_16x16x32_bf16 v[16:19], v[152:155], v[212:215], v[16:19]
	v_mfma_f32_16x16x32_bf16 v[4:7], v[144:147], v[220:223], v[4:7]
	v_mfma_f32_16x16x32_bf16 v[0:3], v[152:155], v[220:223], v[0:3]
	v_mfma_f32_16x16x32_bf16 v[52:55], v[148:151], v[164:167], v[52:55]
	v_mfma_f32_16x16x32_bf16 v[48:51], v[156:159], v[164:167], v[48:51]
	v_mfma_f32_16x16x32_bf16 v[36:39], v[148:151], v[194:197], v[36:39]
	v_mfma_f32_16x16x32_bf16 v[32:35], v[156:159], v[194:197], v[32:35]
	v_mfma_f32_16x16x32_bf16 v[20:23], v[148:151], v[216:219], v[20:23]
	v_mfma_f32_16x16x32_bf16 v[16:19], v[156:159], v[216:219], v[16:19]
	v_mfma_f32_16x16x32_bf16 v[4:7], v[148:151], v[224:227], v[4:7]
	v_mfma_f32_16x16x32_bf16 v[0:3], v[156:159], v[224:227], v[0:3]
	s_setprio 1
	s_barrier
	s_add_i32 s80, 0, 0x18000
	s_add_i32 s81, 0, 0x1c000
	v_add_u32_e32 v140, s80, v206
	v_add_u32_e32 v156, s81, v206
	ds_read_b128 v[128:131], v140
	ds_read_b128 v[132:135], v140 offset:1024
	ds_read_b128 v[136:139], v140 offset:2048
	ds_read_b128 v[140:143], v140 offset:3072
	ds_read_b128 v[144:147], v156
	ds_read_b128 v[148:151], v156 offset:1024
	ds_read_b128 v[152:155], v156 offset:2048
	ds_read_b128 v[156:159], v156 offset:3072
	s_add_u32 s64, s64, s74
	s_addc_u32 s65, s65, 0
	s_mov_b32 m0, s93
	v_lshl_add_u64 v[238:239], s[64:65], 0, v[174:175]
	ds_read_b128 v[160:163], v211 offset:32768
	ds_read_b128 v[164:167], v211 offset:33792
	ds_read_b128 v[190:193], v211 offset:34816
	ds_read_b128 v[194:197], v211 offset:35840
	ds_read_b128 v[212:215], v211 offset:36864
	ds_read_b128 v[216:219], v211 offset:37888
	ds_read_b128 v[220:223], v211 offset:38912
	ds_read_b128 v[224:227], v211 offset:39936
	global_load_lds_dwordx4 v[238:239], off
	v_lshl_add_u64 v[238:239], s[64:65], 0, v[178:179]
	s_mov_b32 m0, s94
	s_nop 0
	global_load_lds_dwordx4 v[238:239], off
	s_waitcnt vmcnt(8)
	s_waitcnt lgkmcnt(0)
	s_barrier
	s_setprio 2
	s_waitcnt lgkmcnt(0)
	v_mfma_f32_16x16x32_bf16 v[124:127], v[128:131], v[160:163], v[124:127]
	v_mfma_f32_16x16x32_bf16 v[120:123], v[136:139], v[160:163], v[120:123]
	v_mfma_f32_16x16x32_bf16 v[108:111], v[128:131], v[190:193], v[108:111]
	v_mfma_f32_16x16x32_bf16 v[104:107], v[136:139], v[190:193], v[104:107]
	v_mfma_f32_16x16x32_bf16 v[92:95], v[128:131], v[212:215], v[92:95]
	v_mfma_f32_16x16x32_bf16 v[88:91], v[136:139], v[212:215], v[88:91]
	v_mfma_f32_16x16x32_bf16 v[76:79], v[128:131], v[220:223], v[76:79]
	v_mfma_f32_16x16x32_bf16 v[72:75], v[136:139], v[220:223], v[72:75]
	v_mfma_f32_16x16x32_bf16 v[124:127], v[132:135], v[164:167], v[124:127]
	v_mfma_f32_16x16x32_bf16 v[120:123], v[140:143], v[164:167], v[120:123]
	v_mfma_f32_16x16x32_bf16 v[108:111], v[132:135], v[194:197], v[108:111]
	v_mfma_f32_16x16x32_bf16 v[104:107], v[140:143], v[194:197], v[104:107]
	v_mfma_f32_16x16x32_bf16 v[92:95], v[132:135], v[216:219], v[92:95]
	v_mfma_f32_16x16x32_bf16 v[88:91], v[140:143], v[216:219], v[88:91]
	v_mfma_f32_16x16x32_bf16 v[76:79], v[132:135], v[224:227], v[76:79]
	v_mfma_f32_16x16x32_bf16 v[72:75], v[140:143], v[224:227], v[72:75]
	s_setprio 1
	s_setprio 2
	v_mfma_f32_16x16x32_bf16 v[116:119], v[144:147], v[160:163], v[116:119]
	v_mfma_f32_16x16x32_bf16 v[112:115], v[152:155], v[160:163], v[112:115]
	v_mfma_f32_16x16x32_bf16 v[100:103], v[144:147], v[190:193], v[100:103]
	v_mfma_f32_16x16x32_bf16 v[96:99], v[152:155], v[190:193], v[96:99]
	v_mfma_f32_16x16x32_bf16 v[84:87], v[144:147], v[212:215], v[84:87]
	v_mfma_f32_16x16x32_bf16 v[80:83], v[152:155], v[212:215], v[80:83]
	v_mfma_f32_16x16x32_bf16 v[68:71], v[144:147], v[220:223], v[68:71]
	v_mfma_f32_16x16x32_bf16 v[64:67], v[152:155], v[220:223], v[64:67]
	v_mfma_f32_16x16x32_bf16 v[116:119], v[148:151], v[164:167], v[116:119]
	v_mfma_f32_16x16x32_bf16 v[112:115], v[156:159], v[164:167], v[112:115]
	v_mfma_f32_16x16x32_bf16 v[100:103], v[148:151], v[194:197], v[100:103]
	v_mfma_f32_16x16x32_bf16 v[96:99], v[156:159], v[194:197], v[96:99]
	v_mfma_f32_16x16x32_bf16 v[84:87], v[148:151], v[216:219], v[84:87]
	v_mfma_f32_16x16x32_bf16 v[80:83], v[156:159], v[216:219], v[80:83]
	v_mfma_f32_16x16x32_bf16 v[68:71], v[148:151], v[224:227], v[68:71]
	v_mfma_f32_16x16x32_bf16 v[64:67], v[156:159], v[224:227], v[64:67]
	s_setprio 1
	s_barrier
	s_add_i32 s64, s80, s72
	v_lshl_add_u64 v[198:199], v[198:199], 0, s[88:89]
	s_mov_b32 m0, s64
	ds_read_b128 v[160:163], v211 offset:49152
	ds_read_b128 v[164:167], v211 offset:50176
	ds_read_b128 v[190:193], v211 offset:51200
	ds_read_b128 v[194:197], v211 offset:52224
	ds_read_b128 v[212:215], v211 offset:53248
	ds_read_b128 v[216:219], v211 offset:54272
	ds_read_b128 v[220:223], v211 offset:55296
	ds_read_b128 v[224:227], v211 offset:56320
	global_load_lds_dwordx4 v[198:199], off
	v_lshl_add_u64 v[198:199], v[228:229], 0, s[88:89]
	s_add_i32 m0, s64, 0x2000
	s_add_i32 s64, s81, s72
	global_load_lds_dwordx4 v[198:199], off
	v_lshl_add_u64 v[198:199], v[230:231], 0, s[88:89]
	s_mov_b32 m0, s64
	s_nop 0
	global_load_lds_dwordx4 v[198:199], off
	v_lshl_add_u64 v[198:199], v[232:233], 0, s[88:89]
	s_add_i32 m0, s64, 0x2000
	s_nop 0
	global_load_lds_dwordx4 v[198:199], off
	v_lshl_add_u64 v[198:199], v[234:235], 0, s[88:89]
	s_mov_b32 m0, s95
	s_nop 0
	global_load_lds_dwordx4 v[198:199], off
	v_lshl_add_u64 v[198:199], v[236:237], 0, s[88:89]
	s_mov_b32 m0, s98
	s_nop 0
	global_load_lds_dwordx4 v[198:199], off
	s_waitcnt vmcnt(8)
	s_waitcnt lgkmcnt(0)
	s_barrier
	s_setprio 2
	s_waitcnt lgkmcnt(0)
	v_mfma_f32_16x16x32_bf16 v[60:63], v[128:131], v[160:163], v[60:63]
	v_mfma_f32_16x16x32_bf16 v[56:59], v[136:139], v[160:163], v[56:59]
	v_mfma_f32_16x16x32_bf16 v[44:47], v[128:131], v[190:193], v[44:47]
	v_mfma_f32_16x16x32_bf16 v[40:43], v[136:139], v[190:193], v[40:43]
	v_mfma_f32_16x16x32_bf16 v[28:31], v[128:131], v[212:215], v[28:31]
	v_mfma_f32_16x16x32_bf16 v[24:27], v[136:139], v[212:215], v[24:27]
	v_mfma_f32_16x16x32_bf16 v[12:15], v[128:131], v[220:223], v[12:15]
	v_mfma_f32_16x16x32_bf16 v[8:11], v[136:139], v[220:223], v[8:11]
	v_mfma_f32_16x16x32_bf16 v[60:63], v[132:135], v[164:167], v[60:63]
	v_mfma_f32_16x16x32_bf16 v[56:59], v[140:143], v[164:167], v[56:59]
	v_mfma_f32_16x16x32_bf16 v[44:47], v[132:135], v[194:197], v[44:47]
	v_mfma_f32_16x16x32_bf16 v[40:43], v[140:143], v[194:197], v[40:43]
	v_mfma_f32_16x16x32_bf16 v[28:31], v[132:135], v[216:219], v[28:31]
	v_mfma_f32_16x16x32_bf16 v[24:27], v[140:143], v[216:219], v[24:27]
	v_mfma_f32_16x16x32_bf16 v[12:15], v[132:135], v[224:227], v[12:15]
	v_mfma_f32_16x16x32_bf16 v[8:11], v[140:143], v[224:227], v[8:11]
	s_setprio 1
	s_setprio 2
	v_mfma_f32_16x16x32_bf16 v[52:55], v[144:147], v[160:163], v[52:55]
	v_mfma_f32_16x16x32_bf16 v[48:51], v[152:155], v[160:163], v[48:51]
	v_mfma_f32_16x16x32_bf16 v[36:39], v[144:147], v[190:193], v[36:39]
	v_mfma_f32_16x16x32_bf16 v[32:35], v[152:155], v[190:193], v[32:35]
	v_mfma_f32_16x16x32_bf16 v[20:23], v[144:147], v[212:215], v[20:23]
	v_mfma_f32_16x16x32_bf16 v[16:19], v[152:155], v[212:215], v[16:19]
	v_mfma_f32_16x16x32_bf16 v[4:7], v[144:147], v[220:223], v[4:7]
	v_mfma_f32_16x16x32_bf16 v[0:3], v[152:155], v[220:223], v[0:3]
	v_mfma_f32_16x16x32_bf16 v[52:55], v[148:151], v[164:167], v[52:55]
	v_mfma_f32_16x16x32_bf16 v[48:51], v[156:159], v[164:167], v[48:51]
	v_mfma_f32_16x16x32_bf16 v[36:39], v[148:151], v[194:197], v[36:39]
	v_mfma_f32_16x16x32_bf16 v[32:35], v[156:159], v[194:197], v[32:35]
	v_mfma_f32_16x16x32_bf16 v[20:23], v[148:151], v[216:219], v[20:23]
	v_mfma_f32_16x16x32_bf16 v[16:19], v[156:159], v[216:219], v[16:19]
	v_mfma_f32_16x16x32_bf16 v[4:7], v[148:151], v[224:227], v[4:7]
	v_mfma_f32_16x16x32_bf16 v[0:3], v[156:159], v[224:227], v[0:3]
	s_setprio 1
	s_barrier
	s_add_u32 s8, s8, 0x100
	s_addc_u32 s9, s9, 0
	s_add_u32 s16, s16, 0x100
	s_addc_u32 s68, s68, 0
	s_cmp_ge_u32 s69, s96
	s_mov_b32 s64, s69
	s_cbranch_scc0 .Lgemm_raised
	s_setprio 0
.Lgemm_done:
	s_and_b64 vcc, exec, s[12:13]
	s_cbranch_vccnz .LBB0_336
	s_cmp_lt_i32 s35, 2
	s_mov_b64 s[8:9], -1
	s_cbranch_scc0 .LBB0_337
